# attention item epilogues (NSA and SWA): z loads and y stores coalesced through a per-wave LDS transpose; SWA's eight serialized load-wait pairs issued together
# speedup vs baseline: 1.0155x; 1.0046x over previous
; DI unsigned pack2(float a, float b) { fv2 v = {a, b}; return __builtin_bit_cast(unsigned, __builtin_convertvector(v, bfv2)); }
; DI float bflo(unsigned u) { return __uint_as_float(u << 16); }
; DI float bfhi(unsigned u) { return __uint_as_float(u & 0xffff0000u); }
; DI float siluf_(float x) { return x * __builtin_amdgcn_rcpf(1.f + __expf(-x)); }
; DI float xor32_sum(float x) { auto r = __builtin_amdgcn_permlane32_swap(__float_as_uint(x), __float_as_uint(x), false, false); return __uint_as_float(r[0]) + __uint_as_float(r[1]); }
; DI void nsa_item(const Params& p, int l_, int item, char* smraw, bool wr = true) {
;     ...
;   lt = xor32_sum(l);
;   inv = (lt > 0.f) ? 1.f / lt : 0.f;
; #pragma unroll
;   for (int e = 0; e < 16; ++e) { ot[0][e] += g1 * inv * o[0][e]; ot[1][e] += g1 * inv * o[1][e]; }
; #pragma unroll
;   for (int dt = 0; dt < 2; ++dt)
; #pragma unroll
;     for (int q = 0; q < 4; ++q) {
;       const int d = 32 * dt + 8 * q + 4 * h;
;       bf16_t* zp = hw + mrow * HS + C_AZ + H * 64 + d;
;       const uint2 z = *(const uint2*)zp;
;       uint2 ov;
;       ov.x = pack2(ot[dt][4 * q] * siluf_(bflo(z.x)), ot[dt][4 * q + 1] * siluf_(bfhi(z.x)));
;       ov.y = pack2(ot[dt][4 * q + 2] * siluf_(bflo(z.y)), ot[dt][4 * q + 3] * siluf_(bfhi(z.y)));
;       if (wr) *(uint2*)zp = ov;
;     }
.Lpf_nsa:
	s_or_b64 exec, exec, s[98:99]
	v_readlane_b32 s0, v252, 62
	v_readlane_b32 s1, v252, 63
	s_movk_i32 s2, 0x1e00
	v_lshlrev_b32_e32 v0, 1, v234
	v_mov_b64_e32 v[2:3], s[0:1]
	v_mad_u64_u32 v[2:3], s[0:1], v210, s2, v[2:3]
	v_mad_i32_i24 v3, v211, s2, v3
	v_lshl_add_u64 v[2:3], v[2:3], 0, v[0:1]
	v_lshlrev_b32_e32 v0, 3, v230
	v_lshl_add_u64 v[2:3], v[2:3], 0, v[0:1]
	s_mov_b32 s0, 0x32a4000
	v_add_co_u32_e32 v10, vcc, s0, v2
	s_mov_b64 s[0:1], 0x32a4f00
	s_nop 0
	v_addc_co_u32_e32 v11, vcc, 0, v3, vcc
	v_lshl_add_u64 v[2:3], v[2:3], 0, s[0:1]
	s_nop 1
	v_readfirstlane_b32 s100, v2
	v_readfirstlane_b32 s101, v3
	v_and_b32_e32 v134, 63, v201
	v_lshrrev_b32_e32 v135, 3, v134
	v_and_b32_e32 v134, 7, v134
	s_movk_i32 s98, 0x1e00
	v_mul_u32_u24_e32 v135, s98, v135
	v_lshl_add_u32 v134, v134, 4, v135
	global_load_dwordx4 v[6:9], v134, s[100:101]
	s_add_u32 s100, s100, 0xf000
	s_addc_u32 s101, s101, 0
	global_load_dwordx4 v[12:15], v134, s[100:101]
	s_add_u32 s100, s100, 0xf000
	s_addc_u32 s101, s101, 0
	global_load_dwordx4 v[16:19], v134, s[100:101]
	s_add_u32 s100, s100, 0xf000
	s_addc_u32 s101, s101, 0
	global_load_dwordx4 v[130:133], v134, s[100:101]
	s_sub_u32 s100, s100, 0x2d000
	s_subb_u32 s101, s101, 0
	v_lshlrev_b32_e32 v4, 16, v231
	v_lshlrev_b32_e32 v5, 16, v232
	v_mul_f32_e32 v4, 0xbfb8aa3b, v4
	v_mul_f32_e32 v5, 0xbfb8aa3b, v5
	v_exp_f32_e32 v4, v4
	v_exp_f32_e32 v5, v5
	v_mov_b32_e32 v212, v214
	v_lshlrev_b32_e32 v0, 16, v233
	v_add_f32_e32 v24, 1.0, v4
	v_add_f32_e32 v25, 1.0, v5
	v_permlane32_swap_b32_e32 v214, v212
	v_mul_f32_e32 v0, 0xbfb8aa3b, v0
	v_pk_add_f32 v[20:21], v[214:215], v[212:213]
	v_exp_f32_e32 v0, v0
	v_div_scale_f32 v22, s[0:1], v21, v21, 1.0
	v_div_scale_f32 v26, s[0:1], v20, v20, 1.0
	v_rcp_f32_e32 v28, v22
	v_rcp_f32_e32 v29, v26
	v_add_f32_e32 v0, 1.0, v0
	v_rcp_f32_e32 v30, v0
	v_rcp_f32_e32 v0, v24
	v_fma_f32 v24, -v22, v28, 1.0
	v_div_scale_f32 v23, vcc, 1.0, v21, 1.0
	v_rcp_f32_e32 v31, v25
	v_fma_f32 v25, -v26, v29, 1.0
	v_fmac_f32_e32 v28, v24, v28
	v_div_scale_f32 v27, s[36:37], 1.0, v20, 1.0
	v_fmac_f32_e32 v29, v25, v29
	v_mul_f32_e32 v128, v23, v28
	v_mul_f32_e32 v129, v27, v29
	v_fma_f32 v24, -v22, v128, v23
	v_fma_f32 v25, -v26, v129, v27
	v_fmac_f32_e32 v128, v24, v28
	v_fmac_f32_e32 v129, v25, v29
	v_fma_f32 v22, -v22, v128, v23
	v_fma_f32 v23, -v26, v129, v27
	v_div_fmas_f32 v22, v22, v28, v128
	s_mov_b64 vcc, s[36:37]
	v_div_fixup_f32 v22, v22, v21, 1.0
	v_div_fmas_f32 v23, v23, v29, v129
	v_cmp_lt_f32_e32 vcc, 0, v21
	v_mul_f32_e32 v0, v0, v235
	v_div_fixup_f32 v23, v23, v20, 1.0
	v_cndmask_b32_e32 v21, 0, v22, vcc
	v_cmp_lt_f32_e32 vcc, 0, v20
	v_mul_f32_e32 v22, v30, v21
	v_cndmask_b32_e32 v20, 0, v23, vcc
	v_mul_f32_e32 v20, v31, v20
	s_movk_i32 s87, 0x1e00
	s_mov_b64 s[2:3], 0
	v_readlane_b32 s23, v251, 0
	v_and_b32_e32 v28, 63, v201
	v_lshrrev_b32_e32 v27, 6, v201
	v_lshrrev_b32_e32 v29, 3, v28
	v_and_b32_e32 v30, 7, v28
	s_movk_i32 s36, 0x2200
	v_mul_u32_u24_e32 v27, s36, v27
	v_add_u32_e32 v27, 0x4800, v27
	s_movk_i32 s36, 0x110
	v_mad_u32_u24 v25, v29, s36, v27
	v_lshl_add_u32 v25, v30, 5, v25
	v_and_b32_e32 v29, 31, v28
	v_lshrrev_b32_e32 v30, 5, v28
	v_mad_u32_u24 v24, v29, s36, v27
	v_lshl_add_u32 v24, v30, 4, v24
	v_pk_mul_f32 v[64:65], v[64:65], v[0:1] op_sel_hi:[1,0]
	v_pk_mul_f32 v[66:67], v[66:67], v[0:1] op_sel_hi:[1,0]
	v_pk_mul_f32 v[68:69], v[68:69], v[0:1] op_sel_hi:[1,0]
	v_pk_mul_f32 v[70:71], v[70:71], v[0:1] op_sel_hi:[1,0]
	v_pk_mul_f32 v[72:73], v[72:73], v[0:1] op_sel_hi:[1,0]
	v_pk_mul_f32 v[74:75], v[74:75], v[0:1] op_sel_hi:[1,0]
	v_pk_mul_f32 v[76:77], v[76:77], v[0:1] op_sel_hi:[1,0]
	v_pk_mul_f32 v[78:79], v[78:79], v[0:1] op_sel_hi:[1,0]
	v_pk_mul_f32 v[80:81], v[80:81], v[0:1] op_sel_hi:[1,0]
	v_pk_mul_f32 v[82:83], v[82:83], v[0:1] op_sel_hi:[1,0]
	v_pk_mul_f32 v[84:85], v[84:85], v[0:1] op_sel_hi:[1,0]
	v_pk_mul_f32 v[86:87], v[86:87], v[0:1] op_sel_hi:[1,0]
	v_pk_mul_f32 v[88:89], v[88:89], v[0:1] op_sel_hi:[1,0]
	v_pk_mul_f32 v[90:91], v[90:91], v[0:1] op_sel_hi:[1,0]
	v_pk_mul_f32 v[92:93], v[92:93], v[0:1] op_sel_hi:[1,0]
	v_pk_mul_f32 v[94:95], v[94:95], v[0:1] op_sel_hi:[1,0]
	v_pk_fma_f32 v[64:65], v[32:33], v[22:23], v[64:65] op_sel_hi:[1,0,1]
	v_pk_fma_f32 v[66:67], v[34:35], v[22:23], v[66:67] op_sel_hi:[1,0,1]
	v_pk_fma_f32 v[68:69], v[36:37], v[22:23], v[68:69] op_sel_hi:[1,0,1]
	v_pk_fma_f32 v[70:71], v[38:39], v[22:23], v[70:71] op_sel_hi:[1,0,1]
	v_pk_fma_f32 v[72:73], v[40:41], v[22:23], v[72:73] op_sel_hi:[1,0,1]
	v_pk_fma_f32 v[74:75], v[42:43], v[22:23], v[74:75] op_sel_hi:[1,0,1]
	v_pk_fma_f32 v[76:77], v[44:45], v[22:23], v[76:77] op_sel_hi:[1,0,1]
	v_pk_fma_f32 v[78:79], v[46:47], v[22:23], v[78:79] op_sel_hi:[1,0,1]
	v_pk_fma_f32 v[80:81], v[48:49], v[22:23], v[80:81] op_sel_hi:[1,0,1]
	v_pk_fma_f32 v[82:83], v[50:51], v[22:23], v[82:83] op_sel_hi:[1,0,1]
	v_pk_fma_f32 v[84:85], v[52:53], v[22:23], v[84:85] op_sel_hi:[1,0,1]
	v_pk_fma_f32 v[86:87], v[54:55], v[22:23], v[86:87] op_sel_hi:[1,0,1]
	v_pk_fma_f32 v[88:89], v[56:57], v[22:23], v[88:89] op_sel_hi:[1,0,1]
	v_pk_fma_f32 v[90:91], v[58:59], v[22:23], v[90:91] op_sel_hi:[1,0,1]
	v_pk_fma_f32 v[92:93], v[60:61], v[22:23], v[92:93] op_sel_hi:[1,0,1]
	v_pk_fma_f32 v[94:95], v[62:63], v[22:23], v[94:95] op_sel_hi:[1,0,1]
	v_pk_fma_f32 v[64:65], v[96:97], v[20:21], v[64:65] op_sel_hi:[1,0,1]
	v_pk_fma_f32 v[66:67], v[98:99], v[20:21], v[66:67] op_sel_hi:[1,0,1]
	v_pk_fma_f32 v[68:69], v[100:101], v[20:21], v[68:69] op_sel_hi:[1,0,1]
	v_pk_fma_f32 v[70:71], v[102:103], v[20:21], v[70:71] op_sel_hi:[1,0,1]
	v_pk_fma_f32 v[72:73], v[104:105], v[20:21], v[72:73] op_sel_hi:[1,0,1]
	v_pk_fma_f32 v[74:75], v[106:107], v[20:21], v[74:75] op_sel_hi:[1,0,1]
	v_pk_fma_f32 v[76:77], v[108:109], v[20:21], v[76:77] op_sel_hi:[1,0,1]
	v_pk_fma_f32 v[78:79], v[110:111], v[20:21], v[78:79] op_sel_hi:[1,0,1]
	v_pk_fma_f32 v[80:81], v[112:113], v[20:21], v[80:81] op_sel_hi:[1,0,1]
	v_pk_fma_f32 v[82:83], v[114:115], v[20:21], v[82:83] op_sel_hi:[1,0,1]
	v_pk_fma_f32 v[84:85], v[116:117], v[20:21], v[84:85] op_sel_hi:[1,0,1]
	v_pk_fma_f32 v[86:87], v[118:119], v[20:21], v[86:87] op_sel_hi:[1,0,1]
	v_pk_fma_f32 v[88:89], v[120:121], v[20:21], v[88:89] op_sel_hi:[1,0,1]
	v_pk_fma_f32 v[90:91], v[122:123], v[20:21], v[90:91] op_sel_hi:[1,0,1]
	v_pk_fma_f32 v[92:93], v[124:125], v[20:21], v[92:93] op_sel_hi:[1,0,1]
	v_pk_fma_f32 v[94:95], v[126:127], v[20:21], v[94:95] op_sel_hi:[1,0,1]
	ds_write_b128 v24, v[64:67]
	ds_write_b128 v24, v[68:71] offset:32
	ds_write_b128 v24, v[72:75] offset:64
	ds_write_b128 v24, v[76:79] offset:96
	ds_write_b128 v24, v[80:83] offset:128
	ds_write_b128 v24, v[84:87] offset:160
	ds_write_b128 v24, v[88:91] offset:192
	ds_write_b128 v24, v[92:95] offset:224
	s_waitcnt lgkmcnt(0)
; DI unsigned pack2(float a, float b) { fv2 v = {a, b}; return __builtin_bit_cast(unsigned, __builtin_convertvector(v, bfv2)); }
; DI float bflo(unsigned u) { return __uint_as_float(u << 16); }
; DI float bfhi(unsigned u) { return __uint_as_float(u & 0xffff0000u); }
; DI float siluf_(float x) { return x * __builtin_amdgcn_rcpf(1.f + __expf(-x)); }
; DI void nsa_item(const Params& p, int l_, int item, char* smraw, bool wr = true) {
;     ...
;   for (int dt = 0; dt < 2; ++dt)
; #pragma unroll
;     for (int q = 0; q < 4; ++q) {
;       const int d = 32 * dt + 8 * q + 4 * h;
;       bf16_t* zp = hw + mrow * HS + C_AZ + H * 64 + d;
;       const uint2 z = *(const uint2*)zp;
;       uint2 ov;
;       ov.x = pack2(ot[dt][4 * q] * siluf_(bflo(z.x)), ot[dt][4 * q + 1] * siluf_(bfhi(z.x)));
;       ov.y = pack2(ot[dt][4 * q + 2] * siluf_(bflo(z.y)), ot[dt][4 * q + 3] * siluf_(bfhi(z.y)));
;       if (wr) *(uint2*)zp = ov;
	ds_read_b128 v[48:51], v25 offset:0
	ds_read_b128 v[52:55], v25 offset:16
	s_waitcnt vmcnt(3)
	v_lshlrev_b32_e32 v32, 16, v6
	v_and_b32_e32 v33, 0xffff0000, v6
	v_lshlrev_b32_e32 v34, 16, v7
	v_and_b32_e32 v35, 0xffff0000, v7
	v_lshlrev_b32_e32 v36, 16, v8
	v_and_b32_e32 v37, 0xffff0000, v8
	v_lshlrev_b32_e32 v38, 16, v9
	v_and_b32_e32 v39, 0xffff0000, v9
	v_mul_f32_e32 v40, 0xbfb8aa3b, v32
	v_mul_f32_e32 v41, 0xbfb8aa3b, v33
	v_mul_f32_e32 v42, 0xbfb8aa3b, v34
	v_mul_f32_e32 v43, 0xbfb8aa3b, v35
	v_mul_f32_e32 v44, 0xbfb8aa3b, v36
	v_mul_f32_e32 v45, 0xbfb8aa3b, v37
	v_mul_f32_e32 v46, 0xbfb8aa3b, v38
	v_mul_f32_e32 v47, 0xbfb8aa3b, v39
	v_exp_f32_e32 v40, v40
	v_exp_f32_e32 v41, v41
	v_exp_f32_e32 v42, v42
	v_exp_f32_e32 v43, v43
	v_exp_f32_e32 v44, v44
	v_exp_f32_e32 v45, v45
	v_exp_f32_e32 v46, v46
	v_exp_f32_e32 v47, v47
	v_add_f32_e32 v40, 1.0, v40
	v_add_f32_e32 v41, 1.0, v41
	v_add_f32_e32 v42, 1.0, v42
	v_add_f32_e32 v43, 1.0, v43
	v_add_f32_e32 v44, 1.0, v44
	v_add_f32_e32 v45, 1.0, v45
	v_add_f32_e32 v46, 1.0, v46
	v_add_f32_e32 v47, 1.0, v47
	v_rcp_f32_e32 v40, v40
	v_rcp_f32_e32 v41, v41
	v_rcp_f32_e32 v42, v42
	v_rcp_f32_e32 v43, v43
	v_rcp_f32_e32 v44, v44
	v_rcp_f32_e32 v45, v45
	v_rcp_f32_e32 v46, v46
	v_rcp_f32_e32 v47, v47
	v_pk_mul_f32 v[32:33], v[40:41], v[32:33]
	v_pk_mul_f32 v[34:35], v[42:43], v[34:35]
	v_pk_mul_f32 v[36:37], v[44:45], v[36:37]
	v_pk_mul_f32 v[38:39], v[46:47], v[38:39]
	s_waitcnt lgkmcnt(0)
	v_pk_mul_f32 v[32:33], v[48:49], v[32:33]
	v_pk_mul_f32 v[34:35], v[50:51], v[34:35]
	v_pk_mul_f32 v[36:37], v[52:53], v[36:37]
	v_pk_mul_f32 v[38:39], v[54:55], v[38:39]
	v_cvt_pk_bf16_f32 v56, v32, v33
	v_cvt_pk_bf16_f32 v57, v34, v35
	v_cvt_pk_bf16_f32 v58, v36, v37
	v_cvt_pk_bf16_f32 v59, v38, v39
	global_store_dwordx4 v134, v[56:59], s[100:101]
	s_nop 1
	s_add_u32 s100, s100, 0xf000
	s_addc_u32 s101, s101, 0
	ds_read_b128 v[48:51], v25 offset:2176
	ds_read_b128 v[52:55], v25 offset:2192
	s_waitcnt vmcnt(3)
	v_lshlrev_b32_e32 v32, 16, v12
	v_and_b32_e32 v33, 0xffff0000, v12
	v_lshlrev_b32_e32 v34, 16, v13
	v_and_b32_e32 v35, 0xffff0000, v13
	v_lshlrev_b32_e32 v36, 16, v14
	v_and_b32_e32 v37, 0xffff0000, v14
	v_lshlrev_b32_e32 v38, 16, v15
	v_and_b32_e32 v39, 0xffff0000, v15
	v_mul_f32_e32 v40, 0xbfb8aa3b, v32
	v_mul_f32_e32 v41, 0xbfb8aa3b, v33
	v_mul_f32_e32 v42, 0xbfb8aa3b, v34
	v_mul_f32_e32 v43, 0xbfb8aa3b, v35
	v_mul_f32_e32 v44, 0xbfb8aa3b, v36
	v_mul_f32_e32 v45, 0xbfb8aa3b, v37
	v_mul_f32_e32 v46, 0xbfb8aa3b, v38
	v_mul_f32_e32 v47, 0xbfb8aa3b, v39
	v_exp_f32_e32 v40, v40
	v_exp_f32_e32 v41, v41
	v_exp_f32_e32 v42, v42
	v_exp_f32_e32 v43, v43
	v_exp_f32_e32 v44, v44
	v_exp_f32_e32 v45, v45
	v_exp_f32_e32 v46, v46
	v_exp_f32_e32 v47, v47
	v_add_f32_e32 v40, 1.0, v40
	v_add_f32_e32 v41, 1.0, v41
	v_add_f32_e32 v42, 1.0, v42
	v_add_f32_e32 v43, 1.0, v43
	v_add_f32_e32 v44, 1.0, v44
	v_add_f32_e32 v45, 1.0, v45
	v_add_f32_e32 v46, 1.0, v46
	v_add_f32_e32 v47, 1.0, v47
	v_rcp_f32_e32 v40, v40
	v_rcp_f32_e32 v41, v41
	v_rcp_f32_e32 v42, v42
	v_rcp_f32_e32 v43, v43
	v_rcp_f32_e32 v44, v44
	v_rcp_f32_e32 v45, v45
	v_rcp_f32_e32 v46, v46
	v_rcp_f32_e32 v47, v47
	v_pk_mul_f32 v[32:33], v[40:41], v[32:33]
	v_pk_mul_f32 v[34:35], v[42:43], v[34:35]
	v_pk_mul_f32 v[36:37], v[44:45], v[36:37]
	v_pk_mul_f32 v[38:39], v[46:47], v[38:39]
	s_waitcnt lgkmcnt(0)
	v_pk_mul_f32 v[32:33], v[48:49], v[32:33]
	v_pk_mul_f32 v[34:35], v[50:51], v[34:35]
	v_pk_mul_f32 v[36:37], v[52:53], v[36:37]
	v_pk_mul_f32 v[38:39], v[54:55], v[38:39]
	v_cvt_pk_bf16_f32 v56, v32, v33
	v_cvt_pk_bf16_f32 v57, v34, v35
	v_cvt_pk_bf16_f32 v58, v36, v37
	v_cvt_pk_bf16_f32 v59, v38, v39
	global_store_dwordx4 v134, v[56:59], s[100:101]
	s_nop 1
	s_add_u32 s100, s100, 0xf000
	s_addc_u32 s101, s101, 0
	ds_read_b128 v[48:51], v25 offset:4352
	ds_read_b128 v[52:55], v25 offset:4368
	s_waitcnt vmcnt(3)
; DI unsigned pack2(float a, float b) { fv2 v = {a, b}; return __builtin_bit_cast(unsigned, __builtin_convertvector(v, bfv2)); }
; DI float bflo(unsigned u) { return __uint_as_float(u << 16); }
; DI float bfhi(unsigned u) { return __uint_as_float(u & 0xffff0000u); }
; DI float siluf_(float x) { return x * __builtin_amdgcn_rcpf(1.f + __expf(-x)); }
; DI void nsa_item(const Params& p, int l_, int item, char* smraw, bool wr = true) {
;     ...
;   for (int dt = 0; dt < 2; ++dt)
; #pragma unroll
;     for (int q = 0; q < 4; ++q) {
;       const int d = 32 * dt + 8 * q + 4 * h;
;       bf16_t* zp = hw + mrow * HS + C_AZ + H * 64 + d;
;       const uint2 z = *(const uint2*)zp;
;       uint2 ov;
;       ov.x = pack2(ot[dt][4 * q] * siluf_(bflo(z.x)), ot[dt][4 * q + 1] * siluf_(bfhi(z.x)));
;       ov.y = pack2(ot[dt][4 * q + 2] * siluf_(bflo(z.y)), ot[dt][4 * q + 3] * siluf_(bfhi(z.y)));
;       if (wr) *(uint2*)zp = ov;
;     }
;   __syncthreads();
	v_lshlrev_b32_e32 v32, 16, v16
	v_and_b32_e32 v33, 0xffff0000, v16
	v_lshlrev_b32_e32 v34, 16, v17
	v_and_b32_e32 v35, 0xffff0000, v17
	v_lshlrev_b32_e32 v36, 16, v18
	v_and_b32_e32 v37, 0xffff0000, v18
	v_lshlrev_b32_e32 v38, 16, v19
	v_and_b32_e32 v39, 0xffff0000, v19
	v_mul_f32_e32 v40, 0xbfb8aa3b, v32
	v_mul_f32_e32 v41, 0xbfb8aa3b, v33
	v_mul_f32_e32 v42, 0xbfb8aa3b, v34
	v_mul_f32_e32 v43, 0xbfb8aa3b, v35
	v_mul_f32_e32 v44, 0xbfb8aa3b, v36
	v_mul_f32_e32 v45, 0xbfb8aa3b, v37
	v_mul_f32_e32 v46, 0xbfb8aa3b, v38
	v_mul_f32_e32 v47, 0xbfb8aa3b, v39
	v_exp_f32_e32 v40, v40
	v_exp_f32_e32 v41, v41
	v_exp_f32_e32 v42, v42
	v_exp_f32_e32 v43, v43
	v_exp_f32_e32 v44, v44
	v_exp_f32_e32 v45, v45
	v_exp_f32_e32 v46, v46
	v_exp_f32_e32 v47, v47
	v_add_f32_e32 v40, 1.0, v40
	v_add_f32_e32 v41, 1.0, v41
	v_add_f32_e32 v42, 1.0, v42
	v_add_f32_e32 v43, 1.0, v43
	v_add_f32_e32 v44, 1.0, v44
	v_add_f32_e32 v45, 1.0, v45
	v_add_f32_e32 v46, 1.0, v46
	v_add_f32_e32 v47, 1.0, v47
	v_rcp_f32_e32 v40, v40
	v_rcp_f32_e32 v41, v41
	v_rcp_f32_e32 v42, v42
	v_rcp_f32_e32 v43, v43
	v_rcp_f32_e32 v44, v44
	v_rcp_f32_e32 v45, v45
	v_rcp_f32_e32 v46, v46
	v_rcp_f32_e32 v47, v47
	v_pk_mul_f32 v[32:33], v[40:41], v[32:33]
	v_pk_mul_f32 v[34:35], v[42:43], v[34:35]
	v_pk_mul_f32 v[36:37], v[44:45], v[36:37]
	v_pk_mul_f32 v[38:39], v[46:47], v[38:39]
	s_waitcnt lgkmcnt(0)
	v_pk_mul_f32 v[32:33], v[48:49], v[32:33]
	v_pk_mul_f32 v[34:35], v[50:51], v[34:35]
	v_pk_mul_f32 v[36:37], v[52:53], v[36:37]
	v_pk_mul_f32 v[38:39], v[54:55], v[38:39]
	v_cvt_pk_bf16_f32 v56, v32, v33
	v_cvt_pk_bf16_f32 v57, v34, v35
	v_cvt_pk_bf16_f32 v58, v36, v37
	v_cvt_pk_bf16_f32 v59, v38, v39
	global_store_dwordx4 v134, v[56:59], s[100:101]
	s_nop 1
	s_add_u32 s100, s100, 0xf000
	s_addc_u32 s101, s101, 0
	ds_read_b128 v[48:51], v25 offset:6528
	ds_read_b128 v[52:55], v25 offset:6544
	s_waitcnt vmcnt(3)
	v_lshlrev_b32_e32 v32, 16, v130
	v_and_b32_e32 v33, 0xffff0000, v130
	v_lshlrev_b32_e32 v34, 16, v131
	v_and_b32_e32 v35, 0xffff0000, v131
	v_lshlrev_b32_e32 v36, 16, v132
	v_and_b32_e32 v37, 0xffff0000, v132
	v_lshlrev_b32_e32 v38, 16, v133
	v_and_b32_e32 v39, 0xffff0000, v133
	v_mul_f32_e32 v40, 0xbfb8aa3b, v32
	v_mul_f32_e32 v41, 0xbfb8aa3b, v33
	v_mul_f32_e32 v42, 0xbfb8aa3b, v34
	v_mul_f32_e32 v43, 0xbfb8aa3b, v35
	v_mul_f32_e32 v44, 0xbfb8aa3b, v36
	v_mul_f32_e32 v45, 0xbfb8aa3b, v37
	v_mul_f32_e32 v46, 0xbfb8aa3b, v38
	v_mul_f32_e32 v47, 0xbfb8aa3b, v39
	v_exp_f32_e32 v40, v40
	v_exp_f32_e32 v41, v41
	v_exp_f32_e32 v42, v42
	v_exp_f32_e32 v43, v43
	v_exp_f32_e32 v44, v44
	v_exp_f32_e32 v45, v45
	v_exp_f32_e32 v46, v46
	v_exp_f32_e32 v47, v47
	v_add_f32_e32 v40, 1.0, v40
	v_add_f32_e32 v41, 1.0, v41
	v_add_f32_e32 v42, 1.0, v42
	v_add_f32_e32 v43, 1.0, v43
	v_add_f32_e32 v44, 1.0, v44
	v_add_f32_e32 v45, 1.0, v45
	v_add_f32_e32 v46, 1.0, v46
	v_add_f32_e32 v47, 1.0, v47
	v_rcp_f32_e32 v40, v40
	v_rcp_f32_e32 v41, v41
	v_rcp_f32_e32 v42, v42
	v_rcp_f32_e32 v43, v43
	v_rcp_f32_e32 v44, v44
	v_rcp_f32_e32 v45, v45
	v_rcp_f32_e32 v46, v46
	v_rcp_f32_e32 v47, v47
	v_pk_mul_f32 v[32:33], v[40:41], v[32:33]
	v_pk_mul_f32 v[34:35], v[42:43], v[34:35]
	v_pk_mul_f32 v[36:37], v[44:45], v[36:37]
	v_pk_mul_f32 v[38:39], v[46:47], v[38:39]
	s_waitcnt lgkmcnt(0)
	v_pk_mul_f32 v[32:33], v[48:49], v[32:33]
	v_pk_mul_f32 v[34:35], v[50:51], v[34:35]
	v_pk_mul_f32 v[36:37], v[52:53], v[36:37]
	v_pk_mul_f32 v[38:39], v[54:55], v[38:39]
	v_cvt_pk_bf16_f32 v56, v32, v33
	v_cvt_pk_bf16_f32 v57, v34, v35
	v_cvt_pk_bf16_f32 v58, v36, v37
	v_cvt_pk_bf16_f32 v59, v38, v39
	global_store_dwordx4 v134, v[56:59], s[100:101]
	s_nop 1
	s_waitcnt lgkmcnt(0)
	s_barrier

; DI unsigned pack2(float a, float b) { fv2 v = {a, b}; return __builtin_bit_cast(unsigned, __builtin_convertvector(v, bfv2)); }
; DI float bflo(unsigned u) { return __uint_as_float(u << 16); }
; DI float bfhi(unsigned u) { return __uint_as_float(u & 0xffff0000u); }
; DI float siluf_(float x) { return x * __builtin_amdgcn_rcpf(1.f + __expf(-x)); }
; DI float xor32_sum(float x) { auto r = __builtin_amdgcn_permlane32_swap(__float_as_uint(x), __float_as_uint(x), false, false); return __uint_as_float(r[0]) + __uint_as_float(r[1]); }
; DI void swa_item(const Params& p, int l_, int item, char* smraw, bool wr = true) {
;     ...
;   const float lt = xor32_sum(l);
;   const float inv = (lt > 0.f) ? 1.f / lt : 0.f;
; #pragma unroll
;   for (int dt = 0; dt < 2; ++dt)
; #pragma unroll
;     for (int q = 0; q < 4; ++q) {
;       const int d = 32 * dt + 8 * q + 4 * h;
;       bf16_t* zp = hw + mrow * HS + C_BZ + H * 64 + d;
;       const uint2 z = *(const uint2*)zp;
;       uint2 ov;
;       ov.x = pack2(inv * o[dt][4 * q] * siluf_(bflo(z.x)), inv * o[dt][4 * q + 1] * siluf_(bfhi(z.x)));
;       ov.y = pack2(inv * o[dt][4 * q + 2] * siluf_(bflo(z.y)), inv * o[dt][4 * q + 3] * siluf_(bfhi(z.y)));
;       if (wr) *(uint2*)zp = ov;
;     }
.Lpf_swa:
	s_or_b64 exec, exec, s[98:99]
	v_mov_b32_e32 v34, v125
	s_nop 1
	v_permlane32_swap_b32_e32 v125, v34
	v_add_f32_e32 v34, v125, v34
	v_div_scale_f32 v35, s[2:3], v34, v34, 1.0
	v_rcp_f32_e32 v38, v35
	s_movk_i32 s0, 0x1e00
	v_mad_u64_u32 v[36:37], s[2:3], v122, s0, 0
	v_fma_f32 v39, -v35, v38, 1.0
	v_fmac_f32_e32 v38, v39, v38
	v_div_scale_f32 v39, vcc, 1.0, v34, 1.0
	v_mul_f32_e32 v40, v39, v38
	v_mad_i32_i24 v37, v123, s0, v37
	v_lshlrev_b32_e32 v0, 6, v131
	v_fma_f32 v41, -v35, v40, v39
	v_fmac_f32_e32 v40, v41, v38
	v_lshl_add_u64 v[36:37], s[12:13], 0, v[36:37]
	v_lshlrev_b32_e32 v0, 1, v0
	v_fma_f32 v35, -v35, v40, v39
	v_lshl_add_u64 v[36:37], v[36:37], 0, v[0:1]
	v_lshlrev_b32_e32 v0, 3, v130
	v_div_fmas_f32 v35, v35, v38, v40
	v_lshl_add_u64 v[38:39], v[36:37], 0, v[0:1]
	s_mov_b64 s[2:3], 0x32a5700
	s_mov_b32 s0, 0x32a5000
	v_lshl_add_u64 v[36:37], v[38:39], 0, s[2:3]
	s_nop 1
	v_readfirstlane_b32 s100, v36
	v_readfirstlane_b32 s101, v37
	v_and_b32_e32 v176, 63, v201
	v_lshrrev_b32_e32 v177, 3, v176
	v_and_b32_e32 v176, 7, v176
	s_movk_i32 s98, 0x1e00
	v_mul_u32_u24_e32 v177, s98, v177
	v_lshl_add_u32 v176, v176, 4, v177
	global_load_dwordx4 v[42:45], v176, s[100:101]
	s_add_u32 s100, s100, 0xf000
	s_addc_u32 s101, s101, 0
	global_load_dwordx4 v[46:49], v176, s[100:101]
	s_add_u32 s100, s100, 0xf000
	s_addc_u32 s101, s101, 0
	global_load_dwordx4 v[50:53], v176, s[100:101]
	s_add_u32 s100, s100, 0xf000
	s_addc_u32 s101, s101, 0
	global_load_dwordx4 v[172:175], v176, s[100:101]
	s_sub_u32 s100, s100, 0x2d000
	s_subb_u32 s101, s101, 0
	v_add_co_u32_e32 v38, vcc, s0, v38
	v_cmp_lt_f32_e64 s[36:37], 0, v34
	s_nop 0
	v_addc_co_u32_e32 v39, vcc, 0, v39, vcc
	v_div_fixup_f32 v34, v35, v34, 1.0
	v_cndmask_b32_e64 v34, 0, v34, s[36:37]
	s_movk_i32 s87, 0x1e00
	s_mov_b32 s20, s38
	v_and_b32_e32 v180, 63, v201
	v_lshrrev_b32_e32 v181, 6, v201
	v_lshrrev_b32_e32 v182, 3, v180
	v_and_b32_e32 v183, 7, v180
	s_movk_i32 s98, 0x2200
	v_mul_u32_u24_e32 v181, s98, v181
	v_add_u32_e32 v181, 0x4800, v181
	s_movk_i32 s98, 0x110
	v_mad_u32_u24 v179, v182, s98, v181
	v_lshl_add_u32 v179, v183, 5, v179
	v_and_b32_e32 v182, 31, v180
	v_lshrrev_b32_e32 v183, 5, v180
	v_mad_u32_u24 v178, v182, s98, v181
	v_lshl_add_u32 v178, v183, 4, v178
	v_pk_mul_f32 v[2:3], v[2:3], v[34:35] op_sel_hi:[1,0]
	v_pk_mul_f32 v[4:5], v[4:5], v[34:35] op_sel_hi:[1,0]
	v_pk_mul_f32 v[6:7], v[6:7], v[34:35] op_sel_hi:[1,0]
	v_pk_mul_f32 v[8:9], v[8:9], v[34:35] op_sel_hi:[1,0]
	v_pk_mul_f32 v[10:11], v[10:11], v[34:35] op_sel_hi:[1,0]
	v_pk_mul_f32 v[12:13], v[12:13], v[34:35] op_sel_hi:[1,0]
	v_pk_mul_f32 v[14:15], v[14:15], v[34:35] op_sel_hi:[1,0]
	v_pk_mul_f32 v[16:17], v[16:17], v[34:35] op_sel_hi:[1,0]
	v_pk_mul_f32 v[18:19], v[18:19], v[34:35] op_sel_hi:[1,0]
	v_pk_mul_f32 v[20:21], v[20:21], v[34:35] op_sel_hi:[1,0]
	v_pk_mul_f32 v[22:23], v[22:23], v[34:35] op_sel_hi:[1,0]
	v_pk_mul_f32 v[24:25], v[24:25], v[34:35] op_sel_hi:[1,0]
	v_pk_mul_f32 v[26:27], v[26:27], v[34:35] op_sel_hi:[1,0]
	v_pk_mul_f32 v[28:29], v[28:29], v[34:35] op_sel_hi:[1,0]
	v_pk_mul_f32 v[30:31], v[30:31], v[34:35] op_sel_hi:[1,0]
	v_pk_mul_f32 v[32:33], v[32:33], v[34:35] op_sel_hi:[1,0]
	ds_write_b128 v178, v[2:5]
	ds_write_b128 v178, v[6:9] offset:32
	ds_write_b128 v178, v[10:13] offset:64
	ds_write_b128 v178, v[14:17] offset:96
	ds_write_b128 v178, v[18:21] offset:128
	ds_write_b128 v178, v[22:25] offset:160
	ds_write_b128 v178, v[26:29] offset:192
	ds_write_b128 v178, v[30:33] offset:224
	s_waitcnt lgkmcnt(0)
	ds_read_b128 v[18:21], v179 offset:0
	ds_read_b128 v[22:25], v179 offset:16
	s_waitcnt vmcnt(3)
	v_lshlrev_b32_e32 v2, 16, v42
	v_and_b32_e32 v3, 0xffff0000, v42
	v_lshlrev_b32_e32 v4, 16, v43
	v_and_b32_e32 v5, 0xffff0000, v43
	v_lshlrev_b32_e32 v6, 16, v44
	v_and_b32_e32 v7, 0xffff0000, v44
	v_lshlrev_b32_e32 v8, 16, v45
	v_and_b32_e32 v9, 0xffff0000, v45
	v_mul_f32_e32 v10, 0xbfb8aa3b, v2
	v_mul_f32_e32 v11, 0xbfb8aa3b, v3
	v_mul_f32_e32 v12, 0xbfb8aa3b, v4
	v_mul_f32_e32 v13, 0xbfb8aa3b, v5
	v_mul_f32_e32 v14, 0xbfb8aa3b, v6
	v_mul_f32_e32 v15, 0xbfb8aa3b, v7
	v_mul_f32_e32 v16, 0xbfb8aa3b, v8
	v_mul_f32_e32 v17, 0xbfb8aa3b, v9
	v_exp_f32_e32 v10, v10
	v_exp_f32_e32 v11, v11
	v_exp_f32_e32 v12, v12
	v_exp_f32_e32 v13, v13
	v_exp_f32_e32 v14, v14
	v_exp_f32_e32 v15, v15
	v_exp_f32_e32 v16, v16
	v_exp_f32_e32 v17, v17
	v_add_f32_e32 v10, 1.0, v10
	v_add_f32_e32 v11, 1.0, v11
	v_add_f32_e32 v12, 1.0, v12
	v_add_f32_e32 v13, 1.0, v13
	v_add_f32_e32 v14, 1.0, v14
	v_add_f32_e32 v15, 1.0, v15
	v_add_f32_e32 v16, 1.0, v16
	v_add_f32_e32 v17, 1.0, v17
	v_rcp_f32_e32 v10, v10
	v_rcp_f32_e32 v11, v11
	v_rcp_f32_e32 v12, v12
	v_rcp_f32_e32 v13, v13
	v_rcp_f32_e32 v14, v14
	v_rcp_f32_e32 v15, v15
	v_rcp_f32_e32 v16, v16
	v_rcp_f32_e32 v17, v17
	v_pk_mul_f32 v[2:3], v[10:11], v[2:3]
	v_pk_mul_f32 v[4:5], v[12:13], v[4:5]
	v_pk_mul_f32 v[6:7], v[14:15], v[6:7]
	v_pk_mul_f32 v[8:9], v[16:17], v[8:9]
	s_waitcnt lgkmcnt(0)
	v_pk_mul_f32 v[2:3], v[18:19], v[2:3]
	v_pk_mul_f32 v[4:5], v[20:21], v[4:5]
	v_pk_mul_f32 v[6:7], v[22:23], v[6:7]
	v_pk_mul_f32 v[8:9], v[24:25], v[8:9]
	v_cvt_pk_bf16_f32 v26, v2, v3
	v_cvt_pk_bf16_f32 v27, v4, v5
	v_cvt_pk_bf16_f32 v28, v6, v7
	v_cvt_pk_bf16_f32 v29, v8, v9
	global_store_dwordx4 v176, v[26:29], s[100:101]
	s_nop 1
	s_add_u32 s100, s100, 0xf000
	s_addc_u32 s101, s101, 0
	ds_read_b128 v[18:21], v179 offset:2176
	ds_read_b128 v[22:25], v179 offset:2192
	s_waitcnt vmcnt(3)
; DI unsigned pack2(float a, float b) { fv2 v = {a, b}; return __builtin_bit_cast(unsigned, __builtin_convertvector(v, bfv2)); }
; DI float bflo(unsigned u) { return __uint_as_float(u << 16); }
; DI float bfhi(unsigned u) { return __uint_as_float(u & 0xffff0000u); }
; DI float siluf_(float x) { return x * __builtin_amdgcn_rcpf(1.f + __expf(-x)); }
; DI void swa_item(const Params& p, int l_, int item, char* smraw, bool wr = true) {
;     ...
;   for (int dt = 0; dt < 2; ++dt)
; #pragma unroll
;     for (int q = 0; q < 4; ++q) {
;       const int d = 32 * dt + 8 * q + 4 * h;
;       bf16_t* zp = hw + mrow * HS + C_BZ + H * 64 + d;
;       const uint2 z = *(const uint2*)zp;
;       uint2 ov;
;       ov.x = pack2(inv * o[dt][4 * q] * siluf_(bflo(z.x)), inv * o[dt][4 * q + 1] * siluf_(bfhi(z.x)));
;       ov.y = pack2(inv * o[dt][4 * q + 2] * siluf_(bflo(z.y)), inv * o[dt][4 * q + 3] * siluf_(bfhi(z.y)));
;       if (wr) *(uint2*)zp = ov;
;     }
;   __syncthreads();
	v_lshlrev_b32_e32 v2, 16, v46
	v_and_b32_e32 v3, 0xffff0000, v46
	v_lshlrev_b32_e32 v4, 16, v47
	v_and_b32_e32 v5, 0xffff0000, v47
	v_lshlrev_b32_e32 v6, 16, v48
	v_and_b32_e32 v7, 0xffff0000, v48
	v_lshlrev_b32_e32 v8, 16, v49
	v_and_b32_e32 v9, 0xffff0000, v49
	v_mul_f32_e32 v10, 0xbfb8aa3b, v2
	v_mul_f32_e32 v11, 0xbfb8aa3b, v3
	v_mul_f32_e32 v12, 0xbfb8aa3b, v4
	v_mul_f32_e32 v13, 0xbfb8aa3b, v5
	v_mul_f32_e32 v14, 0xbfb8aa3b, v6
	v_mul_f32_e32 v15, 0xbfb8aa3b, v7
	v_mul_f32_e32 v16, 0xbfb8aa3b, v8
	v_mul_f32_e32 v17, 0xbfb8aa3b, v9
	v_exp_f32_e32 v10, v10
	v_exp_f32_e32 v11, v11
	v_exp_f32_e32 v12, v12
	v_exp_f32_e32 v13, v13
	v_exp_f32_e32 v14, v14
	v_exp_f32_e32 v15, v15
	v_exp_f32_e32 v16, v16
	v_exp_f32_e32 v17, v17
	v_add_f32_e32 v10, 1.0, v10
	v_add_f32_e32 v11, 1.0, v11
	v_add_f32_e32 v12, 1.0, v12
	v_add_f32_e32 v13, 1.0, v13
	v_add_f32_e32 v14, 1.0, v14
	v_add_f32_e32 v15, 1.0, v15
	v_add_f32_e32 v16, 1.0, v16
	v_add_f32_e32 v17, 1.0, v17
	v_rcp_f32_e32 v10, v10
	v_rcp_f32_e32 v11, v11
	v_rcp_f32_e32 v12, v12
	v_rcp_f32_e32 v13, v13
	v_rcp_f32_e32 v14, v14
	v_rcp_f32_e32 v15, v15
	v_rcp_f32_e32 v16, v16
	v_rcp_f32_e32 v17, v17
	v_pk_mul_f32 v[2:3], v[10:11], v[2:3]
	v_pk_mul_f32 v[4:5], v[12:13], v[4:5]
	v_pk_mul_f32 v[6:7], v[14:15], v[6:7]
	v_pk_mul_f32 v[8:9], v[16:17], v[8:9]
	s_waitcnt lgkmcnt(0)
	v_pk_mul_f32 v[2:3], v[18:19], v[2:3]
	v_pk_mul_f32 v[4:5], v[20:21], v[4:5]
	v_pk_mul_f32 v[6:7], v[22:23], v[6:7]
	v_pk_mul_f32 v[8:9], v[24:25], v[8:9]
	v_cvt_pk_bf16_f32 v26, v2, v3
	v_cvt_pk_bf16_f32 v27, v4, v5
	v_cvt_pk_bf16_f32 v28, v6, v7
	v_cvt_pk_bf16_f32 v29, v8, v9
	global_store_dwordx4 v176, v[26:29], s[100:101]
	s_nop 1
	s_add_u32 s100, s100, 0xf000
	s_addc_u32 s101, s101, 0
	ds_read_b128 v[18:21], v179 offset:4352
	ds_read_b128 v[22:25], v179 offset:4368
	s_waitcnt vmcnt(3)
	v_lshlrev_b32_e32 v2, 16, v50
	v_and_b32_e32 v3, 0xffff0000, v50
	v_lshlrev_b32_e32 v4, 16, v51
	v_and_b32_e32 v5, 0xffff0000, v51
	v_lshlrev_b32_e32 v6, 16, v52
	v_and_b32_e32 v7, 0xffff0000, v52
	v_lshlrev_b32_e32 v8, 16, v53
	v_and_b32_e32 v9, 0xffff0000, v53
	v_mul_f32_e32 v10, 0xbfb8aa3b, v2
	v_mul_f32_e32 v11, 0xbfb8aa3b, v3
	v_mul_f32_e32 v12, 0xbfb8aa3b, v4
	v_mul_f32_e32 v13, 0xbfb8aa3b, v5
	v_mul_f32_e32 v14, 0xbfb8aa3b, v6
	v_mul_f32_e32 v15, 0xbfb8aa3b, v7
	v_mul_f32_e32 v16, 0xbfb8aa3b, v8
	v_mul_f32_e32 v17, 0xbfb8aa3b, v9
	v_exp_f32_e32 v10, v10
	v_exp_f32_e32 v11, v11
	v_exp_f32_e32 v12, v12
	v_exp_f32_e32 v13, v13
	v_exp_f32_e32 v14, v14
	v_exp_f32_e32 v15, v15
	v_exp_f32_e32 v16, v16
	v_exp_f32_e32 v17, v17
	v_add_f32_e32 v10, 1.0, v10
	v_add_f32_e32 v11, 1.0, v11
	v_add_f32_e32 v12, 1.0, v12
	v_add_f32_e32 v13, 1.0, v13
	v_add_f32_e32 v14, 1.0, v14
	v_add_f32_e32 v15, 1.0, v15
	v_add_f32_e32 v16, 1.0, v16
	v_add_f32_e32 v17, 1.0, v17
	v_rcp_f32_e32 v10, v10
	v_rcp_f32_e32 v11, v11
	v_rcp_f32_e32 v12, v12
	v_rcp_f32_e32 v13, v13
	v_rcp_f32_e32 v14, v14
	v_rcp_f32_e32 v15, v15
	v_rcp_f32_e32 v16, v16
	v_rcp_f32_e32 v17, v17
	v_pk_mul_f32 v[2:3], v[10:11], v[2:3]
	v_pk_mul_f32 v[4:5], v[12:13], v[4:5]
	v_pk_mul_f32 v[6:7], v[14:15], v[6:7]
	v_pk_mul_f32 v[8:9], v[16:17], v[8:9]
	s_waitcnt lgkmcnt(0)
	v_pk_mul_f32 v[2:3], v[18:19], v[2:3]
	v_pk_mul_f32 v[4:5], v[20:21], v[4:5]
	v_pk_mul_f32 v[6:7], v[22:23], v[6:7]
	v_pk_mul_f32 v[8:9], v[24:25], v[8:9]
	v_cvt_pk_bf16_f32 v26, v2, v3
	v_cvt_pk_bf16_f32 v27, v4, v5
	v_cvt_pk_bf16_f32 v28, v6, v7
	v_cvt_pk_bf16_f32 v29, v8, v9
	global_store_dwordx4 v176, v[26:29], s[100:101]
	s_nop 1
	s_add_u32 s100, s100, 0xf000
	s_addc_u32 s101, s101, 0
	ds_read_b128 v[18:21], v179 offset:6528
	ds_read_b128 v[22:25], v179 offset:6544
	s_waitcnt vmcnt(3)
	v_lshlrev_b32_e32 v2, 16, v172
	v_and_b32_e32 v3, 0xffff0000, v172
	v_lshlrev_b32_e32 v4, 16, v173
	v_and_b32_e32 v5, 0xffff0000, v173
	v_lshlrev_b32_e32 v6, 16, v174
	v_and_b32_e32 v7, 0xffff0000, v174
	v_lshlrev_b32_e32 v8, 16, v175
	v_and_b32_e32 v9, 0xffff0000, v175
	v_mul_f32_e32 v10, 0xbfb8aa3b, v2
	v_mul_f32_e32 v11, 0xbfb8aa3b, v3
	v_mul_f32_e32 v12, 0xbfb8aa3b, v4
	v_mul_f32_e32 v13, 0xbfb8aa3b, v5
	v_mul_f32_e32 v14, 0xbfb8aa3b, v6
	v_mul_f32_e32 v15, 0xbfb8aa3b, v7
	v_mul_f32_e32 v16, 0xbfb8aa3b, v8
	v_mul_f32_e32 v17, 0xbfb8aa3b, v9
	v_exp_f32_e32 v10, v10
	v_exp_f32_e32 v11, v11
	v_exp_f32_e32 v12, v12
	v_exp_f32_e32 v13, v13
	v_exp_f32_e32 v14, v14
	v_exp_f32_e32 v15, v15
	v_exp_f32_e32 v16, v16
	v_exp_f32_e32 v17, v17
	v_add_f32_e32 v10, 1.0, v10
	v_add_f32_e32 v11, 1.0, v11
	v_add_f32_e32 v12, 1.0, v12
	v_add_f32_e32 v13, 1.0, v13
	v_add_f32_e32 v14, 1.0, v14
	v_add_f32_e32 v15, 1.0, v15
	v_add_f32_e32 v16, 1.0, v16
	v_add_f32_e32 v17, 1.0, v17
	v_rcp_f32_e32 v10, v10
	v_rcp_f32_e32 v11, v11
	v_rcp_f32_e32 v12, v12
	v_rcp_f32_e32 v13, v13
	v_rcp_f32_e32 v14, v14
	v_rcp_f32_e32 v15, v15
	v_rcp_f32_e32 v16, v16
	v_rcp_f32_e32 v17, v17
	v_pk_mul_f32 v[2:3], v[10:11], v[2:3]
	v_pk_mul_f32 v[4:5], v[12:13], v[4:5]
	v_pk_mul_f32 v[6:7], v[14:15], v[6:7]
	v_pk_mul_f32 v[8:9], v[16:17], v[8:9]
	s_waitcnt lgkmcnt(0)
	v_pk_mul_f32 v[2:3], v[18:19], v[2:3]
	v_pk_mul_f32 v[4:5], v[20:21], v[4:5]
	v_pk_mul_f32 v[6:7], v[22:23], v[6:7]
	v_pk_mul_f32 v[8:9], v[24:25], v[8:9]
	v_cvt_pk_bf16_f32 v26, v2, v3
	v_cvt_pk_bf16_f32 v27, v4, v5
	v_cvt_pk_bf16_f32 v28, v6, v7
	v_cvt_pk_bf16_f32 v29, v8, v9
	global_store_dwordx4 v176, v[26:29], s[100:101]
	s_nop 1
	s_waitcnt lgkmcnt(0)
	s_barrier
	s_cbranch_execnz .LBB0_512
	s_branch .LBB0_662
